# diff-attention main loop: exps re-spaced over all 16 PV MFMAs (2 per gap) instead of 4 per gap on the first 8 and a bare 8-MFMA tail
# speedup vs baseline: 1.0177x; 1.0068x over previous
.LBB0_478:
	s_waitcnt lgkmcnt(14)
	v_mfma_f32_32x32x16_bf16 v[0:15], v[156:159], v[208:211], v[0:15]
	v_exp_f32_e32 v128, v128
	v_exp_f32_e32 v129, v129
	ds_read_b64_tr_b16 v[92:93], v212 offset:32768
	ds_read_b64_tr_b16 v[94:95], v212 offset:33280
	s_waitcnt lgkmcnt(14)
	v_mfma_f32_32x32x16_bf16 v[48:63], v[156:159], v[204:207], v[48:63]
	v_exp_f32_e32 v132, v132
	v_exp_f32_e32 v133, v133
	ds_read_b64_tr_b16 v[204:205], v212 offset:36864
	ds_read_b64_tr_b16 v[206:207], v212 offset:37376
	v_add_u32_e32 v176, s31, v243
	ds_read_b128 v[80:83], v176
	ds_read_b128 v[196:199], v176 offset:512
	s_waitcnt lgkmcnt(14)
	v_mfma_f32_32x32x16_bf16 v[0:15], v[152:155], v[100:103], v[0:15]
	v_exp_f32_e32 v136, v136
	v_exp_f32_e32 v137, v137
	ds_read_b64_tr_b16 v[100:101], v212 offset:33792
	ds_read_b64_tr_b16 v[102:103], v212 offset:34304
	ds_read_b128 v[200:203], v176 offset:2048
	ds_read_b128 v[192:195], v176 offset:2560
	v_mfma_f32_32x32x16_bf16 v[48:63], v[152:155], v[96:99], v[48:63]
	v_exp_f32_e32 v140, v140
	v_exp_f32_e32 v141, v141
	ds_read_b64_tr_b16 v[96:97], v212 offset:37888
	ds_read_b64_tr_b16 v[98:99], v212 offset:38400
	ds_read_b128 v[188:191], v176 offset:4096
	ds_read_b128 v[184:187], v176 offset:4608
	s_waitcnt lgkmcnt(14)
	v_mfma_f32_32x32x16_bf16 v[0:15], v[148:151], v[108:111], v[0:15]
	v_exp_f32_e32 v112, v112
	v_exp_f32_e32 v113, v113
	ds_read_b64_tr_b16 v[108:109], v212 offset:34816
	ds_read_b64_tr_b16 v[110:111], v212 offset:35328
	ds_read_b128 v[180:183], v176 offset:6144
	ds_read_b128 v[176:179], v176 offset:6656
	v_mfma_f32_32x32x16_bf16 v[48:63], v[148:151], v[104:107], v[48:63]
	v_exp_f32_e32 v116, v116
	v_exp_f32_e32 v117, v117
	ds_read_b64_tr_b16 v[104:105], v212 offset:38912
	ds_read_b64_tr_b16 v[106:107], v212 offset:39424
	v_mfma_f32_32x32x16_bf16 v[0:15], v[144:147], v[84:87], v[0:15]
	v_exp_f32_e32 v120, v120
	v_exp_f32_e32 v121, v121
	ds_read_b64_tr_b16 v[84:85], v212 offset:35840
	ds_read_b64_tr_b16 v[86:87], v212 offset:36352
	v_mfma_f32_32x32x16_bf16 v[48:63], v[144:147], v[88:91], v[48:63]
	v_exp_f32_e32 v124, v124
	v_exp_f32_e32 v125, v125
	ds_read_b64_tr_b16 v[88:89], v212 offset:39936
	ds_read_b64_tr_b16 v[90:91], v212 offset:40448
	s_waitcnt lgkmcnt(14)
	v_mfma_f32_32x32x16_bf16 v[16:31], v[156:159], v[92:95], v[16:31]
	v_exp_f32_e32 v130, v130
	v_exp_f32_e32 v131, v131
	v_mfma_f32_32x32x16_bf16 v[32:47], v[156:159], v[204:207], v[32:47]
	v_exp_f32_e32 v134, v134
	v_exp_f32_e32 v135, v135
	v_mfma_f32_32x32x16_bf16 v[16:31], v[152:155], v[100:103], v[16:31]
	v_exp_f32_e32 v138, v138
	v_exp_f32_e32 v139, v139
	s_waitcnt lgkmcnt(12)
	v_mfma_f32_32x32x16_bf16 v[32:47], v[152:155], v[96:99], v[32:47]
	v_exp_f32_e32 v142, v142
	v_exp_f32_e32 v143, v143
	s_waitcnt lgkmcnt(8)
	v_mfma_f32_32x32x16_bf16 v[16:31], v[148:151], v[108:111], v[16:31]
	v_exp_f32_e32 v114, v114
	v_exp_f32_e32 v115, v115
	s_waitcnt lgkmcnt(4)
	v_mfma_f32_32x32x16_bf16 v[32:47], v[148:151], v[104:107], v[32:47]
	v_exp_f32_e32 v118, v118
	v_exp_f32_e32 v119, v119
	s_waitcnt lgkmcnt(2)
	v_mfma_f32_32x32x16_bf16 v[16:31], v[144:147], v[84:87], v[16:31]
	v_exp_f32_e32 v122, v122
	v_exp_f32_e32 v123, v123
	s_waitcnt lgkmcnt(0)
	v_mfma_f32_32x32x16_bf16 v[32:47], v[144:147], v[88:91], v[32:47]
	v_exp_f32_e32 v126, v126
	v_exp_f32_e32 v127, v127
	s_waitcnt vmcnt(3) lgkmcnt(0)
	s_barrier
	s_andn2_b64 vcc, exec, s[22:23]
	s_cbranch_vccnz .LBB0_480
	s_waitcnt lgkmcnt(0)
	v_add_u32_e32 v96, s18, v247
	ds_read_b128 v[84:87], v96 offset:96
	ds_read_b128 v[88:91], v96 offset:64
	ds_read_b128 v[92:95], v96 offset:32
	ds_read_b128 v[96:99], v96
	s_waitcnt lgkmcnt(3)
	v_pk_mul_f32 v[12:13], v[12:13], v[84:85]
	s_waitcnt lgkmcnt(2)
	v_pk_mul_f32 v[8:9], v[8:9], v[88:89]
	s_waitcnt lgkmcnt(1)
	v_pk_mul_f32 v[4:5], v[4:5], v[92:93]
	v_pk_mul_f32 v[14:15], v[14:15], v[86:87]
	v_pk_mul_f32 v[10:11], v[10:11], v[90:91]
	v_pk_mul_f32 v[6:7], v[6:7], v[94:95]
	s_waitcnt lgkmcnt(0)
	v_pk_mul_f32 v[2:3], v[2:3], v[98:99]
	v_pk_mul_f32 v[0:1], v[0:1], v[96:97]
	v_pk_mul_f32 v[60:61], v[60:61], v[84:85]
	v_pk_mul_f32 v[56:57], v[56:57], v[88:89]
	v_pk_mul_f32 v[52:53], v[52:53], v[92:93]
	v_pk_mul_f32 v[62:63], v[62:63], v[86:87]
	v_pk_mul_f32 v[58:59], v[58:59], v[90:91]
	v_pk_mul_f32 v[54:55], v[54:55], v[94:95]
	v_pk_mul_f32 v[50:51], v[50:51], v[98:99]
	v_pk_mul_f32 v[48:49], v[48:49], v[96:97]
	v_pk_mul_f32 v[28:29], v[28:29], v[84:85]
	v_pk_mul_f32 v[24:25], v[24:25], v[88:89]
	v_pk_mul_f32 v[20:21], v[20:21], v[92:93]
	v_pk_mul_f32 v[30:31], v[30:31], v[86:87]
	v_pk_mul_f32 v[26:27], v[26:27], v[90:91]
	v_pk_mul_f32 v[22:23], v[22:23], v[94:95]
	v_pk_mul_f32 v[18:19], v[18:19], v[98:99]
	v_pk_mul_f32 v[16:17], v[16:17], v[96:97]
	v_pk_mul_f32 v[44:45], v[44:45], v[84:85]
	v_pk_mul_f32 v[40:41], v[40:41], v[88:89]
	v_pk_mul_f32 v[36:37], v[36:37], v[92:93]
	v_pk_mul_f32 v[46:47], v[46:47], v[86:87]
	v_pk_mul_f32 v[42:43], v[42:43], v[90:91]
	v_pk_mul_f32 v[38:39], v[38:39], v[94:95]
	v_pk_mul_f32 v[34:35], v[34:35], v[98:99]
	v_pk_mul_f32 v[32:33], v[32:33], v[96:97]

.LBB0_481:
	s_waitcnt lgkmcnt(14)
	v_mfma_f32_32x32x16_bf16 v[0:15], v[156:159], v[212:215], v[0:15]
	v_exp_f32_e32 v96, v96
	v_exp_f32_e32 v97, v97
	ds_read_b64_tr_b16 v[124:125], v236 offset:32768
	ds_read_b64_tr_b16 v[126:127], v236 offset:33280
	s_waitcnt lgkmcnt(14)
	v_mfma_f32_32x32x16_bf16 v[48:63], v[156:159], v[204:207], v[48:63]
	v_exp_f32_e32 v100, v100
	v_exp_f32_e32 v101, v101
	ds_read_b64_tr_b16 v[136:137], v236 offset:36864
	ds_read_b64_tr_b16 v[138:139], v236 offset:37376
	v_add_u32_e32 v176, s34, v243
	ds_read_b128 v[204:207], v176
	ds_read_b128 v[196:199], v176 offset:512
	s_waitcnt lgkmcnt(14)
	v_mfma_f32_32x32x16_bf16 v[0:15], v[152:155], v[208:211], v[0:15]
	v_exp_f32_e32 v104, v104
	v_exp_f32_e32 v105, v105
	ds_read_b64_tr_b16 v[140:141], v236 offset:33792
	ds_read_b64_tr_b16 v[142:143], v236 offset:34304
	ds_read_b128 v[200:203], v176 offset:2048
	ds_read_b128 v[192:195], v176 offset:2560
	v_mfma_f32_32x32x16_bf16 v[48:63], v[152:155], v[132:135], v[48:63]
	v_exp_f32_e32 v108, v108
	v_exp_f32_e32 v109, v109
	ds_read_b64_tr_b16 v[132:133], v236 offset:37888
	ds_read_b64_tr_b16 v[134:135], v236 offset:38400
	ds_read_b128 v[188:191], v176 offset:4096
	ds_read_b128 v[184:187], v176 offset:4608
	s_waitcnt lgkmcnt(14)
	v_mfma_f32_32x32x16_bf16 v[0:15], v[148:151], v[128:131], v[0:15]
	v_exp_f32_e32 v80, v80
	v_exp_f32_e32 v81, v81
	ds_read_b64_tr_b16 v[128:129], v236 offset:34816
	ds_read_b64_tr_b16 v[130:131], v236 offset:35328
	ds_read_b128 v[180:183], v176 offset:6144
	ds_read_b128 v[176:179], v176 offset:6656
	v_mfma_f32_32x32x16_bf16 v[48:63], v[148:151], v[112:115], v[48:63]
	v_exp_f32_e32 v84, v84
	v_exp_f32_e32 v85, v85
	ds_read_b64_tr_b16 v[112:113], v236 offset:38912
	ds_read_b64_tr_b16 v[114:115], v236 offset:39424
	v_mfma_f32_32x32x16_bf16 v[0:15], v[144:147], v[116:119], v[0:15]
	v_exp_f32_e32 v88, v88
	v_exp_f32_e32 v89, v89
	ds_read_b64_tr_b16 v[116:117], v236 offset:35840
	ds_read_b64_tr_b16 v[118:119], v236 offset:36352
	v_mfma_f32_32x32x16_bf16 v[48:63], v[144:147], v[120:123], v[48:63]
	v_exp_f32_e32 v92, v92
	v_exp_f32_e32 v93, v93
	ds_read_b64_tr_b16 v[120:121], v236 offset:39936
	ds_read_b64_tr_b16 v[122:123], v236 offset:40448
	s_waitcnt lgkmcnt(14)
	v_mfma_f32_32x32x16_bf16 v[16:31], v[156:159], v[124:127], v[16:31]
	v_exp_f32_e32 v98, v98
	v_exp_f32_e32 v99, v99
	v_mfma_f32_32x32x16_bf16 v[32:47], v[156:159], v[136:139], v[32:47]
	v_exp_f32_e32 v102, v102
	v_exp_f32_e32 v103, v103
	v_mfma_f32_32x32x16_bf16 v[16:31], v[152:155], v[140:143], v[16:31]
	v_exp_f32_e32 v106, v106
	v_exp_f32_e32 v107, v107
	s_waitcnt lgkmcnt(12)
	v_mfma_f32_32x32x16_bf16 v[32:47], v[152:155], v[132:135], v[32:47]
	v_exp_f32_e32 v110, v110
	v_exp_f32_e32 v111, v111
	s_waitcnt lgkmcnt(8)
	v_mfma_f32_32x32x16_bf16 v[16:31], v[148:151], v[128:131], v[16:31]
	v_exp_f32_e32 v82, v82
	v_exp_f32_e32 v83, v83
	s_waitcnt lgkmcnt(4)
	v_mfma_f32_32x32x16_bf16 v[32:47], v[148:151], v[112:115], v[32:47]
	v_exp_f32_e32 v86, v86
	v_exp_f32_e32 v87, v87
	s_waitcnt lgkmcnt(2)
	v_mfma_f32_32x32x16_bf16 v[16:31], v[144:147], v[116:119], v[16:31]
	v_exp_f32_e32 v90, v90
	v_exp_f32_e32 v91, v91
	s_waitcnt lgkmcnt(0)
	v_mfma_f32_32x32x16_bf16 v[32:47], v[144:147], v[120:123], v[32:47]
	v_exp_f32_e32 v94, v94
	v_exp_f32_e32 v95, v95
	s_waitcnt vmcnt(3) lgkmcnt(0)
	s_barrier
	s_andn2_b64 vcc, exec, s[22:23]
	s_cbranch_vccnz .LBB0_483
	s_waitcnt lgkmcnt(0)
	v_add_u32_e32 v124, s18, v247
	ds_read_b128 v[112:115], v124 offset:96
	ds_read_b128 v[116:119], v124 offset:64
	ds_read_b128 v[120:123], v124 offset:32
	ds_read_b128 v[124:127], v124
	s_waitcnt lgkmcnt(3)
	v_pk_mul_f32 v[12:13], v[12:13], v[112:113]
	s_waitcnt lgkmcnt(2)
	v_pk_mul_f32 v[8:9], v[8:9], v[116:117]
	s_waitcnt lgkmcnt(1)
	v_pk_mul_f32 v[4:5], v[4:5], v[120:121]
	v_pk_mul_f32 v[14:15], v[14:15], v[114:115]
	v_pk_mul_f32 v[10:11], v[10:11], v[118:119]
	v_pk_mul_f32 v[6:7], v[6:7], v[122:123]
	s_waitcnt lgkmcnt(0)
	v_pk_mul_f32 v[2:3], v[2:3], v[126:127]
	v_pk_mul_f32 v[0:1], v[0:1], v[124:125]
	v_pk_mul_f32 v[60:61], v[60:61], v[112:113]
	v_pk_mul_f32 v[56:57], v[56:57], v[116:117]
	v_pk_mul_f32 v[52:53], v[52:53], v[120:121]
	v_pk_mul_f32 v[62:63], v[62:63], v[114:115]
	v_pk_mul_f32 v[58:59], v[58:59], v[118:119]
	v_pk_mul_f32 v[54:55], v[54:55], v[122:123]
	v_pk_mul_f32 v[50:51], v[50:51], v[126:127]
	v_pk_mul_f32 v[48:49], v[48:49], v[124:125]
	v_pk_mul_f32 v[28:29], v[28:29], v[112:113]
	v_pk_mul_f32 v[24:25], v[24:25], v[116:117]
	v_pk_mul_f32 v[20:21], v[20:21], v[120:121]
	v_pk_mul_f32 v[30:31], v[30:31], v[114:115]
	v_pk_mul_f32 v[26:27], v[26:27], v[118:119]
	v_pk_mul_f32 v[22:23], v[22:23], v[122:123]
	v_pk_mul_f32 v[18:19], v[18:19], v[126:127]
	v_pk_mul_f32 v[16:17], v[16:17], v[124:125]
	v_pk_mul_f32 v[44:45], v[44:45], v[112:113]
	v_pk_mul_f32 v[40:41], v[40:41], v[116:117]
	v_pk_mul_f32 v[36:37], v[36:37], v[120:121]
	v_pk_mul_f32 v[46:47], v[46:47], v[114:115]
	v_pk_mul_f32 v[42:43], v[42:43], v[118:119]
	v_pk_mul_f32 v[38:39], v[38:39], v[122:123]
	v_pk_mul_f32 v[34:35], v[34:35], v[126:127]
	v_pk_mul_f32 v[32:33], v[32:33], v[124:125]
